# conv item LN: parameters loaded once per item, row gate loads hoisted above the reductions, counted waits (plus conv halo batching and the two GEMM epilogue pipelines)
# speedup vs baseline: 1.0332x; 1.0104x over previous
; __device__ __forceinline__ void conv_item(KP p, LAS unsigned char* lds, int l, int tile) {
;     ...
;     unsigned nv[4];
; #pragma unroll
;     for (int q = 0; q < 4; ++q) nv[q] = *(const unsigned*)(hm + (size_t)(tbase + q) * HMW + C_GLU);
;     const float* lng = p->in[12] + l * 1024; const float* lnb = p->in[13] + l * 1024;
;     ...
;         for (int j = 0; j < 4; ++j) { const int c = lane * 4 + 256 * j;
;             const f32x4 gg = *(const f32x4*)(lng + c), bb = *(const f32x4*)(lnb + c);
.LBB0_460:
	s_mul_i32 s6, s6, 0x84000
	v_lshl_add_u64 v[4:5], s[6:7], 1, v[82:83]
	v_add_co_u32_e32 v8, vcc, 0x3000, v4
	v_lshl_add_u32 v175, v2, 2, 0
	s_nop 0
	v_addc_co_u32_e32 v9, vcc, 0, v5, vcc
	global_load_dword v174, v[8:9], off offset:512
	v_add_co_u32_e32 v8, vcc, 0x7000, v4
	v_and_b32_e32 v2, 64, v172
	s_nop 0
	v_addc_co_u32_e32 v9, vcc, 0, v5, vcc
	global_load_dword v177, v[8:9], off offset:1024
	v_add_co_u32_e32 v8, vcc, 0xb000, v4
	v_add_u32_e32 v2, 64, v2
	s_nop 0
	v_addc_co_u32_e32 v9, vcc, 0, v5, vcc
	v_add_co_u32_e32 v4, vcc, 0xf000, v4
	global_load_dword v184, v[8:9], off offset:1536
	s_nop 0
	v_addc_co_u32_e32 v5, vcc, 0, v5, vcc
	global_load_dword v185, v[4:5], off offset:2048
	v_xor_b32_e32 v4, 1, v172
	v_cmp_lt_i32_e32 vcc, v4, v2
	s_load_dwordx4 s[40:43], s[0:1], 0x60
	v_and_b32_e32 v3, 63, v6
	v_cndmask_b32_e32 v4, v172, v4, vcc
	v_lshlrev_b32_e32 v176, 2, v4
	v_xor_b32_e32 v4, 2, v172
	v_cmp_lt_i32_e32 vcc, v4, v2
	s_waitcnt lgkmcnt(0)
	s_add_u32 s40, s40, s44
	s_addc_u32 s41, s41, s45
	v_cndmask_b32_e32 v4, v172, v4, vcc
	v_lshlrev_b32_e32 v178, 2, v4
	v_xor_b32_e32 v4, 4, v172
	v_cmp_lt_i32_e32 vcc, v4, v2
	s_add_u32 s42, s42, s44
	s_addc_u32 s43, s43, s45
	v_cndmask_b32_e32 v4, v172, v4, vcc
	v_lshlrev_b32_e32 v179, 2, v4
	v_xor_b32_e32 v4, 8, v172
	v_cmp_lt_i32_e32 vcc, v4, v2
	s_ashr_i32 s6, s24, 4
	s_and_b32 s46, s6, -4
	v_cndmask_b32_e32 v4, v172, v4, vcc
	v_lshlrev_b32_e32 v180, 2, v4
	v_xor_b32_e32 v4, 16, v172
	s_lshl_b32 s6, s6, 12
	v_lshlrev_b32_e32 v0, 4, v3
	v_cmp_lt_i32_e32 vcc, v4, v2
	s_and_b32 s6, s6, 0xffffc000
	v_lshl_add_u64 v[152:153], s[40:41], 0, v[0:1]
	v_cndmask_b32_e32 v4, v172, v4, vcc
	s_add_i32 s6, s6, 0
	v_readlane_b32 s40, v240, 39
	v_lshlrev_b32_e32 v181, 2, v4
	v_xor_b32_e32 v4, 32, v172
	v_lshl_add_u64 v[154:155], s[42:43], 0, v[0:1]
	v_add_u32_e32 v183, s6, v0
	v_lshlrev_b32_e32 v0, 3, v3
	v_readlane_b32 s41, v240, 40
	v_cmp_lt_i32_e32 vcc, v4, v2
	s_lshl_b32 s62, s92, 6
	v_lshl_add_u64 v[156:157], s[40:41], 0, v[0:1]
	v_readlane_b32 s40, v240, 41
	v_cndmask_b32_e32 v2, v172, v4, vcc
	v_readlane_b32 s41, v240, 42
	s_mov_b32 s63, 0
	v_lshlrev_b32_e32 v182, 2, v2
	s_add_i32 s47, s62, 0xffff9004
	s_ashr_i32 s61, s46, 31
	s_addk_i32 s62, 0x9000
	v_lshl_add_u64 v[158:159], s[40:41], 0, v[0:1]
	global_load_dwordx4 v[196:199], v[152:153], off
	global_load_dwordx4 v[200:203], v[154:155], off
	global_load_dwordx4 v[204:207], v[152:153], off offset:1024
	global_load_dwordx4 v[208:211], v[154:155], off offset:1024
	global_load_dwordx4 v[212:215], v[152:153], off offset:2048
	global_load_dwordx4 v[216:219], v[154:155], off offset:2048
	global_load_dwordx4 v[220:223], v[152:153], off offset:3072
	global_load_dwordx4 v[224:227], v[154:155], off offset:3072
	s_mov_b64 s[44:45], -1
	s_mov_b64 s[42:43], 0

; #define LAS __attribute__((address_space(3)))
; __device__ __forceinline__ void conv_item(KP p, LAS unsigned char* lds, int l, int tile) {
;     ...
;     for (int tt = 0; tt < 4; ++tt) { const int o = wid * 4 + tt; const size_t tok = (size_t)t0 + o;
;         f32x4 v[4]; float sm = 0.f;
; #pragma unroll
;         for (int j = 0; j < 4; ++j) { v[j] = *(const LAS f32x4*)(ybuf + o * 1024 + lane * 4 + 256 * j); sm += (v[j][0] + v[j][1]) + (v[j][2] + v[j][3]); }
;         const float mean = wave_sum(sm) * (1.f / 1024.f); float sq = 0.f;
; #pragma unroll
;         for (int j = 0; j < 4; ++j) { v[j] = v[j] - mean; sq += (v[j][0] * v[j][0] + v[j][1] * v[j][1]) + (v[j][2] * v[j][2] + v[j][3] * v[j][3]); }
;         const float rstd = rsqrtf(wave_sum(sq) * (1.f / 1024.f) + LN_EPS);
;     ...
;             const u32x2 gt = *(const u32x2*)(HM + tok * HMW + C_DGATE + c);
.LBB0_464:
	v_add_u32_e32 v0, s6, v183
	ds_read_b128 v[14:17], v0
	ds_read_b128 v[10:13], v0 offset:1024
	ds_read_b128 v[6:9], v0 offset:2048
	s_mov_b64 s[42:43], 0x4200
	s_addk_i32 s6, 0x1000
	global_load_dwordx2 v[228:229], v[160:161], off offset:-1024
	global_load_dwordx2 v[230:231], v[160:161], off offset:-512
	global_load_dwordx2 v[232:233], v[160:161], off
	global_load_dwordx2 v[234:235], v[160:161], off offset:512
	v_lshl_add_u64 v[160:161], v[160:161], 0, s[42:43]
	s_waitcnt lgkmcnt(2)
	v_mov_b32_e32 v2, v15
	v_mov_b32_e32 v3, v16
	v_mov_b32_e32 v4, v14
	v_mov_b32_e32 v5, v17
	v_pk_add_f32 v[2:3], v[2:3], v[4:5]
	s_waitcnt lgkmcnt(1)
	v_mov_b32_e32 v4, v10
	v_add_f32_e32 v2, v2, v3
	v_add_f32_e32 v164, 0, v2
	v_mov_b32_e32 v2, v11
	v_mov_b32_e32 v3, v12
	v_mov_b32_e32 v5, v13
	v_pk_add_f32 v[2:3], v[2:3], v[4:5]
	s_cmpk_eq_i32 s6, 0x4000
	v_pk_add_f32 v[186:187], v[2:3], v[2:3] op_sel:[0,1] op_sel_hi:[1,0]
	ds_read_b128 v[2:5], v0 offset:3072
	s_waitcnt lgkmcnt(1)
	v_add_f32_e32 v188, v6, v7
	v_add_f32_e32 v190, v8, v9
	s_waitcnt lgkmcnt(0)
	v_mov_b32_e32 v165, v2
	v_mov_b32_e32 v187, v3
	v_mov_b32_e32 v189, v4
	v_mov_b32_e32 v191, v5
	v_pk_add_f32 v[164:165], v[164:165], v[186:187]
	v_pk_add_f32 v[186:187], v[188:189], v[190:191]
	s_nop 0
	v_pk_add_f32 v[164:165], v[164:165], v[186:187]
	s_nop 0
	v_add_f32_e32 v0, v164, v165
	ds_bpermute_b32 v164, v176, v0
	s_waitcnt lgkmcnt(0)
	v_add_f32_e32 v0, v0, v164
	ds_bpermute_b32 v164, v178, v0
	s_waitcnt lgkmcnt(0)
	v_add_f32_e32 v0, v0, v164
	ds_bpermute_b32 v164, v179, v0
	s_waitcnt lgkmcnt(0)
	v_add_f32_e32 v0, v0, v164
	ds_bpermute_b32 v164, v180, v0
	s_waitcnt lgkmcnt(0)
	v_add_f32_e32 v0, v0, v164
	ds_bpermute_b32 v164, v181, v0
	s_waitcnt lgkmcnt(0)
	v_add_f32_e32 v0, v0, v164
	ds_bpermute_b32 v164, v182, v0
	s_waitcnt lgkmcnt(0)
	v_add_f32_e32 v192, v0, v164
	v_fmamk_f32 v15, v192, 0xba800000, v15
	v_fmamk_f32 v14, v192, 0xba800000, v14
	v_fmamk_f32 v17, v192, 0xba800000, v17
	v_fmac_f32_e32 v16, 0xba800000, v192
	v_pk_mul_f32 v[164:165], v[16:17], v[16:17]
	v_pk_mul_f32 v[186:187], v[14:15], v[14:15]
	v_fmamk_f32 v11, v192, 0xba800000, v11
	v_pk_mov_b32 v[188:189], v[186:187], v[164:165] op_sel:[1,0]
	v_mov_b32_e32 v187, v165
	v_fmamk_f32 v10, v192, 0xba800000, v10
	v_fmamk_f32 v13, v192, 0xba800000, v13
	v_fmac_f32_e32 v12, 0xba800000, v192
	v_pk_add_f32 v[164:165], v[188:189], v[186:187]
	v_pk_mul_f32 v[186:187], v[12:13], v[12:13]
	v_pk_mul_f32 v[188:189], v[10:11], v[10:11]
	v_fmamk_f32 v6, v192, 0xba800000, v6
	v_pk_mov_b32 v[190:191], v[188:189], v[186:187] op_sel:[1,0]
	v_mov_b32_e32 v189, v187
	v_fmamk_f32 v7, v192, 0xba800000, v7
	v_fmac_f32_e32 v8, 0xba800000, v192
	v_mul_f32_e32 v0, v6, v6
	v_pk_add_f32 v[186:187], v[190:191], v[188:189]
	v_fmamk_f32 v9, v192, 0xba800000, v9
	v_pk_fma_f32 v[188:189], v[6:7], v[6:7], v[0:1] op_sel_hi:[1,1,0]
	v_mul_f32_e32 v0, v8, v8
	v_pk_add_f32 v[164:165], v[164:165], v[164:165] op_sel_hi:[0,1]
	v_pk_add_f32 v[186:187], v[186:187], v[186:187] op_sel_hi:[0,1]
	v_pk_fma_f32 v[190:191], v[8:9], v[8:9], v[0:1] op_sel_hi:[1,1,0]
	v_fmamk_f32 v5, v192, 0xba800000, v5
	v_fmamk_f32 v4, v192, 0xba800000, v4
	v_fmamk_f32 v3, v192, 0xba800000, v3
	v_fmac_f32_e32 v2, 0xba800000, v192
	v_mul_f32_e32 v188, v2, v2
	v_mul_f32_e32 v190, v3, v3
	v_mul_f32_e32 v164, v4, v4
	v_mul_f32_e32 v186, v5, v5
	v_pk_add_f32 v[188:189], v[188:189], v[190:191]
	v_pk_add_f32 v[164:165], v[164:165], v[186:187]
	s_nop 0
	v_pk_add_f32 v[164:165], v[188:189], v[164:165]
	s_nop 0
	v_add_f32_e32 v0, v164, v165
	ds_bpermute_b32 v164, v176, v0
	s_waitcnt lgkmcnt(0)
	v_add_f32_e32 v0, v0, v164
	ds_bpermute_b32 v164, v178, v0
	s_waitcnt lgkmcnt(0)
	v_add_f32_e32 v0, v0, v164
	ds_bpermute_b32 v164, v179, v0
	s_waitcnt lgkmcnt(0)
	v_add_f32_e32 v0, v0, v164
	ds_bpermute_b32 v164, v180, v0
	s_waitcnt lgkmcnt(0)
	v_add_f32_e32 v0, v0, v164
	ds_bpermute_b32 v164, v181, v0
	s_waitcnt lgkmcnt(0)
	v_add_f32_e32 v0, v0, v164
	ds_bpermute_b32 v164, v182, v0
	s_waitcnt lgkmcnt(0)
; __device__ __forceinline__ float bflo(unsigned w) { return __uint_as_float(w << 16); }
; __device__ __forceinline__ float bfhi(unsigned w) { return __uint_as_float(w & 0xffff0000u); }
; __device__ __forceinline__ float siluf_(float x) { return x * sigmoidf_(x); }
; __device__ __forceinline__ void conv_item(KP p, LAS unsigned char* lds, int l, int tile) {
;     ...
;         const float rstd = rsqrtf(wave_sum(sq) * (1.f / 1024.f) + LN_EPS);
; #pragma unroll
;         for (int j = 0; j < 4; ++j) { const int c = lane * 4 + 256 * j;
;             const f32x4 gg = *(const f32x4*)(lng + c), bb = *(const f32x4*)(lnb + c);
;             const u32x2 gt = *(const u32x2*)(HM + tok * HMW + C_DGATE + c);
;             const f32x4 y = v[j] * rstd * gg + bb;
;             u32x2 wv; wv.x = pk2(siluf_(y[0]) * bflo(gt.x), siluf_(y[1]) * bfhi(gt.x)); wv.y = pk2(siluf_(y[2]) * bflo(gt.y), siluf_(y[3]) * bfhi(gt.y));
;             *(u32x2*)(YD + tok * 1024 + c) = wv; } }
	v_add_f32_e32 v0, v0, v164
	v_fmamk_f32 v0, v0, 0x3a800000, v169
	v_cmp_gt_f32_e32 vcc, s56, v0
	v_mul_f32_e32 v164, 0x4b800000, v0
	s_nop 0
	v_cndmask_b32_e32 v0, v0, v164, vcc
	v_rsq_f32_e32 v0, v0
	s_nop 0
	v_mul_f32_e32 v164, 0x45800000, v0
	v_cndmask_b32_e32 v0, v0, v164, vcc
	v_pk_mul_f32 v[14:15], v[14:15], v[0:1] op_sel_hi:[1,0]
	v_pk_mul_f32 v[16:17], v[16:17], v[0:1] op_sel_hi:[1,0]
	v_pk_mul_f32 v[10:11], v[10:11], v[0:1] op_sel_hi:[1,0]
	v_pk_mul_f32 v[12:13], v[12:13], v[0:1] op_sel_hi:[1,0]
	v_pk_mul_f32 v[6:7], v[6:7], v[0:1] op_sel_hi:[1,0]
	v_pk_mul_f32 v[8:9], v[8:9], v[0:1] op_sel_hi:[1,0]
	v_pk_mul_f32 v[2:3], v[2:3], v[0:1] op_sel_hi:[1,0]
	v_pk_mul_f32 v[4:5], v[4:5], v[0:1] op_sel_hi:[1,0]
	v_pk_fma_f32 v[14:15], v[196:197], v[14:15], v[200:201]
	v_pk_fma_f32 v[16:17], v[198:199], v[16:17], v[202:203]
	v_mul_f32_e32 v186, 0xbfb8aa3b, v14
	v_mul_f32_e32 v187, 0xbfb8aa3b, v15
	v_mul_f32_e32 v188, 0xbfb8aa3b, v16
	v_mul_f32_e32 v189, 0xbfb8aa3b, v17
	v_exp_f32_e32 v186, v186
	v_exp_f32_e32 v187, v187
	v_exp_f32_e32 v188, v188
	v_exp_f32_e32 v189, v189
	v_add_f32_e32 v186, 1.0, v186
	v_add_f32_e32 v187, 1.0, v187
	v_add_f32_e32 v188, 1.0, v188
	v_add_f32_e32 v189, 1.0, v189
	v_rcp_f32_e32 v186, v186
	v_rcp_f32_e32 v187, v187
	v_rcp_f32_e32 v188, v188
	v_rcp_f32_e32 v189, v189
	s_waitcnt vmcnt(3)
	v_lshlrev_b32_e32 v190, 16, v228
	v_and_b32_e32 v191, 0xffff0000, v228
	v_lshlrev_b32_e32 v192, 16, v229
	v_and_b32_e32 v193, 0xffff0000, v229
	v_pk_mul_f32 v[14:15], v[14:15], v[186:187]
	v_pk_mul_f32 v[16:17], v[16:17], v[188:189]
	v_pk_mul_f32 v[14:15], v[14:15], v[190:191]
	v_pk_mul_f32 v[16:17], v[16:17], v[192:193]
	v_cvt_pk_bf16_f32 v14, v14, v15
	v_cvt_pk_bf16_f32 v15, v16, v17
	global_store_dwordx2 v[162:163], v[14:15], off offset:-1024
	v_pk_fma_f32 v[10:11], v[204:205], v[10:11], v[208:209]
	v_pk_fma_f32 v[12:13], v[206:207], v[12:13], v[210:211]
	v_mul_f32_e32 v186, 0xbfb8aa3b, v10
	v_mul_f32_e32 v187, 0xbfb8aa3b, v11
	v_mul_f32_e32 v188, 0xbfb8aa3b, v12
	v_mul_f32_e32 v189, 0xbfb8aa3b, v13
	v_exp_f32_e32 v186, v186
	v_exp_f32_e32 v187, v187
	v_exp_f32_e32 v188, v188
	v_exp_f32_e32 v189, v189
	v_add_f32_e32 v186, 1.0, v186
	v_add_f32_e32 v187, 1.0, v187
	v_add_f32_e32 v188, 1.0, v188
	v_add_f32_e32 v189, 1.0, v189
	v_rcp_f32_e32 v186, v186
	v_rcp_f32_e32 v187, v187
	v_rcp_f32_e32 v188, v188
	v_rcp_f32_e32 v189, v189
	s_waitcnt vmcnt(3)
	v_lshlrev_b32_e32 v190, 16, v230
	v_and_b32_e32 v191, 0xffff0000, v230
	v_lshlrev_b32_e32 v192, 16, v231
	v_and_b32_e32 v193, 0xffff0000, v231
	v_pk_mul_f32 v[10:11], v[10:11], v[186:187]
	v_pk_mul_f32 v[12:13], v[12:13], v[188:189]
	v_pk_mul_f32 v[10:11], v[10:11], v[190:191]
	v_pk_mul_f32 v[12:13], v[12:13], v[192:193]
	v_cvt_pk_bf16_f32 v10, v10, v11
	v_cvt_pk_bf16_f32 v11, v12, v13
	global_store_dwordx2 v[162:163], v[10:11], off offset:-512
	v_pk_fma_f32 v[6:7], v[212:213], v[6:7], v[216:217]
	v_pk_fma_f32 v[8:9], v[214:215], v[8:9], v[218:219]
	v_mul_f32_e32 v186, 0xbfb8aa3b, v6
	v_mul_f32_e32 v187, 0xbfb8aa3b, v7
	v_mul_f32_e32 v188, 0xbfb8aa3b, v8
	v_mul_f32_e32 v189, 0xbfb8aa3b, v9
	v_exp_f32_e32 v186, v186
	v_exp_f32_e32 v187, v187
	v_exp_f32_e32 v188, v188
	v_exp_f32_e32 v189, v189
	v_add_f32_e32 v186, 1.0, v186
	v_add_f32_e32 v187, 1.0, v187
	v_add_f32_e32 v188, 1.0, v188
	v_add_f32_e32 v189, 1.0, v189
	v_rcp_f32_e32 v186, v186
	v_rcp_f32_e32 v187, v187
	v_rcp_f32_e32 v188, v188
	v_rcp_f32_e32 v189, v189
	s_waitcnt vmcnt(3)
	v_lshlrev_b32_e32 v190, 16, v232
	v_and_b32_e32 v191, 0xffff0000, v232
	v_lshlrev_b32_e32 v192, 16, v233
	v_and_b32_e32 v193, 0xffff0000, v233
	v_pk_mul_f32 v[6:7], v[6:7], v[186:187]
	v_pk_mul_f32 v[8:9], v[8:9], v[188:189]
	v_pk_mul_f32 v[6:7], v[6:7], v[190:191]
	v_pk_mul_f32 v[8:9], v[8:9], v[192:193]
	v_cvt_pk_bf16_f32 v6, v6, v7
	v_cvt_pk_bf16_f32 v7, v8, v9
	global_store_dwordx2 v[162:163], v[6:7], off
	v_pk_fma_f32 v[2:3], v[220:221], v[2:3], v[224:225]
	v_pk_fma_f32 v[4:5], v[222:223], v[4:5], v[226:227]
	v_mul_f32_e32 v186, 0xbfb8aa3b, v2
	v_mul_f32_e32 v187, 0xbfb8aa3b, v3
	v_mul_f32_e32 v188, 0xbfb8aa3b, v4
	v_mul_f32_e32 v189, 0xbfb8aa3b, v5
	v_exp_f32_e32 v186, v186
	v_exp_f32_e32 v187, v187
	v_exp_f32_e32 v188, v188
	v_exp_f32_e32 v189, v189
	v_add_f32_e32 v186, 1.0, v186
	v_add_f32_e32 v187, 1.0, v187
	v_add_f32_e32 v188, 1.0, v188
	v_add_f32_e32 v189, 1.0, v189
	v_rcp_f32_e32 v186, v186
	v_rcp_f32_e32 v187, v187
	v_rcp_f32_e32 v188, v188
	v_rcp_f32_e32 v189, v189
	s_waitcnt vmcnt(3)
	v_lshlrev_b32_e32 v190, 16, v234
	v_and_b32_e32 v191, 0xffff0000, v234
	v_lshlrev_b32_e32 v192, 16, v235
	v_and_b32_e32 v193, 0xffff0000, v235
	v_pk_mul_f32 v[2:3], v[2:3], v[186:187]
	v_pk_mul_f32 v[4:5], v[4:5], v[188:189]
	v_pk_mul_f32 v[2:3], v[2:3], v[190:191]
	v_pk_mul_f32 v[4:5], v[4:5], v[192:193]
	v_cvt_pk_bf16_f32 v2, v2, v3
	v_cvt_pk_bf16_f32 v3, v4, v5
	global_store_dwordx2 v[162:163], v[2:3], off offset:512
	s_mov_b64 s[42:43], 0x800
	v_lshl_add_u64 v[162:163], v[162:163], 0, s[42:43]
	s_cbranch_scc0 .LBB0_464
	s_mov_b32 s63, 32
	s_mov_b64 s[44:45], 0
	s_mov_b64 s[42:43], -1
	s_and_b64 vcc, exec, s[40:41]
	s_barrier
	s_cbranch_vccz .LBB0_461
